# +E16 gd_prep x-initialisation LDS reads issued 8 ahead with counted waits (were pairwise with lgkmcnt(0)); trans-use wait state kept
# baseline (speedup 1.0000x reference)
; #define LAS __attribute__((address_space(3)))
; __device__ __forceinline__ float bf2f(bf16_t v) { return __uint_as_float((unsigned)v << 16); }
; __device__ __forceinline__ void gd_prep_item(CArgs* a, LAS unsigned char* lds, int l, int item) {
;     ...
;         if (col < 128) {
; #pragma unroll
;             for (int t = 0; t < 64; ++t) x[t] = BETA[t] * V[t * 128 + col]; }
;         else {
; #pragma unroll
;             for (int t = 0; t < 64; ++t) x[t] = BETA[t] * __expf(GG[t]) * bf2f(*(const LAS bf16_t*)(lds + OFF_KN + t * PITCH + (col - 128) * 2)); }
.LBB0_984:
	s_andn2_saveexec_b64 s[6:7], s[10:11]
	s_cbranch_execz .LBB0_994
	ds_read_b32 v29, v117 offset:256
	s_movk_i32 s10, 0x7f
	v_cmp_lt_i32_e32 vcc, s10, v3
	s_and_saveexec_b64 s[10:11], vcc
	s_xor_b64 s[10:11], exec, s[10:11]
	s_cbranch_execz .LBB0_987
	ds_read2_b32 v[84:85], v117 offset0:62 offset1:63
	ds_read2_b32 v[88:89], v117 offset1:1
	ds_read2_b32 v[100:101], v117 offset0:2 offset1:3
	ds_read2_b32 v[104:105], v117 offset0:66 offset1:67
	ds_read_b32 v28, v117 offset:260
	v_add_u32_e32 v32, 0, v123
	ds_read_u16 v92, v32 offset:17424
	ds_read_u16 v96, v32 offset:17152
	ds_read_u16 v108, v32 offset:17696
	ds_read_u16 v112, v32 offset:17968
	s_waitcnt lgkmcnt(8)
	v_mul_f32_e32 v22, 0x3fb8aa3b, v84
	s_waitcnt lgkmcnt(7)
	v_mul_f32_e32 v4, 0x3fb8aa3b, v88
	v_exp_f32_e32 v7, v4
	v_mul_f32_e32 v4, 0x3fb8aa3b, v89
	ds_read2_b32 v[88:89], v117 offset0:68 offset1:69
	v_exp_f32_e32 v6, v4
	v_mul_f32_e32 v23, 0x3fb8aa3b, v85
	ds_read2_b32 v[84:85], v117 offset0:4 offset1:5
	v_exp_f32_e32 v22, v22
	v_exp_f32_e32 v23, v23
	s_waitcnt lgkmcnt(6)
	v_pk_mul_f32 v[4:5], v[28:29], v[6:7]
	s_waitcnt lgkmcnt(5)
	v_lshlrev_b32_e32 v6, 16, v92
	ds_read_u16 v92, v32 offset:18240
	s_waitcnt lgkmcnt(5)
	v_lshlrev_b32_e32 v7, 16, v96
	ds_read_u16 v96, v32 offset:18512
	v_pk_mul_f32 v[4:5], v[4:5], v[6:7]
	v_mul_f32_e32 v6, 0x3fb8aa3b, v100
	v_mul_f32_e32 v7, 0x3fb8aa3b, v101
	ds_read2_b32 v[100:101], v117 offset0:6 offset1:7
	v_exp_f32_e32 v6, v6
	v_exp_f32_e32 v7, v7
	s_nop 0
	v_pk_mul_f32 v[6:7], v[104:105], v[6:7]
	ds_read2_b32 v[104:105], v117 offset0:70 offset1:71
	s_waitcnt lgkmcnt(7)
	v_lshlrev_b32_e32 v8, 16, v108
	ds_read_u16 v108, v32 offset:18784
	s_waitcnt lgkmcnt(7)
	v_lshlrev_b32_e32 v9, 16, v112
	ds_read_u16 v112, v32 offset:19056
	v_pk_mul_f32 v[70:71], v[6:7], v[8:9]
	s_waitcnt lgkmcnt(6)
	v_mul_f32_e32 v6, 0x3fb8aa3b, v84
	v_mul_f32_e32 v7, 0x3fb8aa3b, v85
	ds_read2_b32 v[84:85], v117 offset0:8 offset1:9
	v_exp_f32_e32 v6, v6
	v_exp_f32_e32 v7, v7
	s_nop 0
	v_pk_mul_f32 v[6:7], v[88:89], v[6:7]
	ds_read2_b32 v[88:89], v117 offset0:72 offset1:73
	s_waitcnt lgkmcnt(7)
	v_lshlrev_b32_e32 v8, 16, v92
	ds_read_u16 v92, v32 offset:19328
	s_waitcnt lgkmcnt(7)
	v_lshlrev_b32_e32 v9, 16, v96
	ds_read_u16 v96, v32 offset:19600
	v_pk_mul_f32 v[74:75], v[6:7], v[8:9]
	s_waitcnt lgkmcnt(7)
	v_mul_f32_e32 v6, 0x3fb8aa3b, v100
	v_mul_f32_e32 v7, 0x3fb8aa3b, v101
	ds_read2_b32 v[100:101], v117 offset0:10 offset1:11
	v_exp_f32_e32 v6, v6
	v_exp_f32_e32 v7, v7
	s_waitcnt lgkmcnt(7)
	v_pk_mul_f32 v[6:7], v[104:105], v[6:7]
	ds_read2_b32 v[104:105], v117 offset0:74 offset1:75
	s_waitcnt lgkmcnt(7)
	v_lshlrev_b32_e32 v8, 16, v108
	ds_read_u16 v108, v32 offset:19872
	s_waitcnt lgkmcnt(7)
	v_lshlrev_b32_e32 v9, 16, v112
	ds_read_u16 v112, v32 offset:20144
	v_pk_mul_f32 v[80:81], v[6:7], v[8:9]
	s_waitcnt lgkmcnt(7)
	v_mul_f32_e32 v6, 0x3fb8aa3b, v84
	v_mul_f32_e32 v7, 0x3fb8aa3b, v85
	ds_read2_b32 v[84:85], v117 offset0:12 offset1:13
	v_exp_f32_e32 v6, v6
	v_exp_f32_e32 v7, v7
	s_waitcnt lgkmcnt(7)
	v_pk_mul_f32 v[6:7], v[88:89], v[6:7]
	ds_read2_b32 v[88:89], v117 offset0:76 offset1:77
	s_waitcnt lgkmcnt(7)
	v_lshlrev_b32_e32 v8, 16, v92
	ds_read_u16 v92, v32 offset:20416
	s_waitcnt lgkmcnt(7)
	v_lshlrev_b32_e32 v9, 16, v96
	ds_read_u16 v96, v32 offset:20688
	v_pk_mul_f32 v[78:79], v[6:7], v[8:9]
	s_waitcnt lgkmcnt(7)
	v_mul_f32_e32 v6, 0x3fb8aa3b, v100
	v_mul_f32_e32 v7, 0x3fb8aa3b, v101
	ds_read2_b32 v[100:101], v117 offset0:14 offset1:15
	v_exp_f32_e32 v6, v6
	v_exp_f32_e32 v7, v7
	s_waitcnt lgkmcnt(7)
	v_pk_mul_f32 v[6:7], v[104:105], v[6:7]
	ds_read2_b32 v[104:105], v117 offset0:78 offset1:79
	s_waitcnt lgkmcnt(7)
	v_lshlrev_b32_e32 v8, 16, v108
	ds_read_u16 v108, v32 offset:20960
	s_waitcnt lgkmcnt(7)
	v_lshlrev_b32_e32 v9, 16, v112
	ds_read_u16 v112, v32 offset:21232
	v_pk_mul_f32 v[76:77], v[6:7], v[8:9]
	s_waitcnt lgkmcnt(7)
	v_mul_f32_e32 v6, 0x3fb8aa3b, v84
	v_mul_f32_e32 v7, 0x3fb8aa3b, v85
	ds_read2_b32 v[84:85], v117 offset0:16 offset1:17
	v_exp_f32_e32 v6, v6
	v_exp_f32_e32 v7, v7
	s_waitcnt lgkmcnt(7)
	v_pk_mul_f32 v[6:7], v[88:89], v[6:7]
	ds_read2_b32 v[88:89], v117 offset0:80 offset1:81
	s_waitcnt lgkmcnt(7)
	v_lshlrev_b32_e32 v8, 16, v92
	ds_read_u16 v92, v32 offset:21504
	s_waitcnt lgkmcnt(7)
	v_lshlrev_b32_e32 v9, 16, v96
	ds_read_u16 v96, v32 offset:21776
	v_pk_mul_f32 v[72:73], v[6:7], v[8:9]
	s_waitcnt lgkmcnt(7)
	v_mul_f32_e32 v6, 0x3fb8aa3b, v100
	v_mul_f32_e32 v7, 0x3fb8aa3b, v101
	ds_read2_b32 v[100:101], v117 offset0:18 offset1:19
	v_exp_f32_e32 v6, v6
	v_exp_f32_e32 v7, v7
	s_waitcnt lgkmcnt(7)
	v_pk_mul_f32 v[6:7], v[104:105], v[6:7]
	ds_read2_b32 v[104:105], v117 offset0:82 offset1:83
	s_waitcnt lgkmcnt(7)
	v_lshlrev_b32_e32 v8, 16, v108
	ds_read_u16 v108, v32 offset:22048
	s_waitcnt lgkmcnt(7)
	v_lshlrev_b32_e32 v9, 16, v112
	ds_read_u16 v112, v32 offset:22320
	v_pk_mul_f32 v[66:67], v[6:7], v[8:9]
	s_waitcnt lgkmcnt(7)
	v_mul_f32_e32 v6, 0x3fb8aa3b, v84
	v_mul_f32_e32 v7, 0x3fb8aa3b, v85
	ds_read2_b32 v[84:85], v117 offset0:20 offset1:21
	v_exp_f32_e32 v6, v6
	v_exp_f32_e32 v7, v7
	s_waitcnt lgkmcnt(7)
	v_pk_mul_f32 v[6:7], v[88:89], v[6:7]
	ds_read2_b32 v[88:89], v117 offset0:84 offset1:85
	s_waitcnt lgkmcnt(7)
	v_lshlrev_b32_e32 v8, 16, v92
	ds_read_u16 v92, v32 offset:22592
	s_waitcnt lgkmcnt(7)
	v_lshlrev_b32_e32 v9, 16, v96
	ds_read_u16 v96, v32 offset:22864
	v_pk_mul_f32 v[64:65], v[6:7], v[8:9]
	s_waitcnt lgkmcnt(7)
	v_mul_f32_e32 v6, 0x3fb8aa3b, v100
	v_mul_f32_e32 v7, 0x3fb8aa3b, v101
	ds_read2_b32 v[100:101], v117 offset0:22 offset1:23
	v_exp_f32_e32 v6, v6
	v_exp_f32_e32 v7, v7
	s_waitcnt lgkmcnt(7)
; #define LAS __attribute__((address_space(3)))
; __device__ __forceinline__ float bf2f(bf16_t v) { return __uint_as_float((unsigned)v << 16); }
; __device__ __forceinline__ void gd_prep_item(CArgs* a, LAS unsigned char* lds, int l, int item) {
;     ...
; #pragma unroll
;             for (int t = 0; t < 64; ++t) x[t] = BETA[t] * __expf(GG[t]) * bf2f(*(const LAS bf16_t*)(lds + OFF_KN + t * PITCH + (col - 128) * 2)); }
	v_pk_mul_f32 v[6:7], v[104:105], v[6:7]
	ds_read2_b32 v[104:105], v117 offset0:86 offset1:87
	s_waitcnt lgkmcnt(7)
	v_lshlrev_b32_e32 v8, 16, v108
	ds_read_u16 v108, v32 offset:23136
	s_waitcnt lgkmcnt(7)
	v_lshlrev_b32_e32 v9, 16, v112
	ds_read_u16 v112, v32 offset:23408
	v_pk_mul_f32 v[62:63], v[6:7], v[8:9]
	s_waitcnt lgkmcnt(7)
	v_mul_f32_e32 v6, 0x3fb8aa3b, v84
	v_mul_f32_e32 v7, 0x3fb8aa3b, v85
	ds_read2_b32 v[84:85], v117 offset0:24 offset1:25
	v_exp_f32_e32 v6, v6
	v_exp_f32_e32 v7, v7
	s_waitcnt lgkmcnt(7)
	v_pk_mul_f32 v[6:7], v[88:89], v[6:7]
	ds_read2_b32 v[88:89], v117 offset0:88 offset1:89
	s_waitcnt lgkmcnt(7)
	v_lshlrev_b32_e32 v8, 16, v92
	ds_read_u16 v92, v32 offset:23680
	s_waitcnt lgkmcnt(7)
	v_lshlrev_b32_e32 v9, 16, v96
	ds_read_u16 v96, v32 offset:23952
	v_pk_mul_f32 v[60:61], v[6:7], v[8:9]
	s_waitcnt lgkmcnt(7)
	v_mul_f32_e32 v6, 0x3fb8aa3b, v100
	v_mul_f32_e32 v7, 0x3fb8aa3b, v101
	ds_read2_b32 v[100:101], v117 offset0:26 offset1:27
	v_exp_f32_e32 v6, v6
	v_exp_f32_e32 v7, v7
	s_waitcnt lgkmcnt(7)
	v_pk_mul_f32 v[6:7], v[104:105], v[6:7]
	ds_read2_b32 v[104:105], v117 offset0:90 offset1:91
	s_waitcnt lgkmcnt(7)
	v_lshlrev_b32_e32 v8, 16, v108
	ds_read_u16 v108, v32 offset:24224
	s_waitcnt lgkmcnt(7)
	v_lshlrev_b32_e32 v9, 16, v112
	ds_read_u16 v112, v32 offset:24496
	v_pk_mul_f32 v[56:57], v[6:7], v[8:9]
	s_waitcnt lgkmcnt(7)
	v_mul_f32_e32 v6, 0x3fb8aa3b, v84
	v_mul_f32_e32 v7, 0x3fb8aa3b, v85
	ds_read2_b32 v[84:85], v117 offset0:28 offset1:29
	v_exp_f32_e32 v6, v6
	v_exp_f32_e32 v7, v7
	s_waitcnt lgkmcnt(7)
	v_pk_mul_f32 v[6:7], v[88:89], v[6:7]
	ds_read2_b32 v[88:89], v117 offset0:92 offset1:93
	s_waitcnt lgkmcnt(7)
	v_lshlrev_b32_e32 v8, 16, v92
	ds_read_u16 v92, v32 offset:24768
	s_waitcnt lgkmcnt(7)
	v_lshlrev_b32_e32 v9, 16, v96
	ds_read_u16 v96, v32 offset:25040
	v_pk_mul_f32 v[54:55], v[6:7], v[8:9]
	s_waitcnt lgkmcnt(7)
	v_mul_f32_e32 v6, 0x3fb8aa3b, v100
	v_mul_f32_e32 v7, 0x3fb8aa3b, v101
	ds_read2_b32 v[100:101], v117 offset0:30 offset1:31
	v_exp_f32_e32 v6, v6
	v_exp_f32_e32 v7, v7
	s_waitcnt lgkmcnt(7)
	v_pk_mul_f32 v[6:7], v[104:105], v[6:7]
	ds_read2_b32 v[104:105], v117 offset0:94 offset1:95
	s_waitcnt lgkmcnt(7)
	v_lshlrev_b32_e32 v8, 16, v108
	ds_read_u16 v108, v32 offset:25312
	s_waitcnt lgkmcnt(7)
	v_lshlrev_b32_e32 v9, 16, v112
	ds_read_u16 v112, v32 offset:25584
	v_pk_mul_f32 v[52:53], v[6:7], v[8:9]
	s_waitcnt lgkmcnt(7)
	v_mul_f32_e32 v6, 0x3fb8aa3b, v84
	v_mul_f32_e32 v7, 0x3fb8aa3b, v85
	ds_read2_b32 v[84:85], v117 offset0:32 offset1:33
	v_exp_f32_e32 v6, v6
	v_exp_f32_e32 v7, v7
	s_waitcnt lgkmcnt(7)
	v_pk_mul_f32 v[6:7], v[88:89], v[6:7]
	ds_read2_b32 v[88:89], v117 offset0:96 offset1:97
	s_waitcnt lgkmcnt(7)
	v_lshlrev_b32_e32 v8, 16, v92
	ds_read_u16 v92, v32 offset:25856
	s_waitcnt lgkmcnt(7)
	v_lshlrev_b32_e32 v9, 16, v96
	ds_read_u16 v96, v32 offset:26128
	v_pk_mul_f32 v[48:49], v[6:7], v[8:9]
	s_waitcnt lgkmcnt(7)
	v_mul_f32_e32 v6, 0x3fb8aa3b, v100
	v_mul_f32_e32 v7, 0x3fb8aa3b, v101
	ds_read2_b32 v[100:101], v117 offset0:34 offset1:35
	v_exp_f32_e32 v6, v6
	v_exp_f32_e32 v7, v7
	s_waitcnt lgkmcnt(7)
	v_pk_mul_f32 v[6:7], v[104:105], v[6:7]
	ds_read2_b32 v[104:105], v117 offset0:98 offset1:99
	s_waitcnt lgkmcnt(7)
	v_lshlrev_b32_e32 v8, 16, v108
	ds_read_u16 v108, v32 offset:26400
	s_waitcnt lgkmcnt(7)
	v_lshlrev_b32_e32 v9, 16, v112
	ds_read_u16 v112, v32 offset:26672
	v_pk_mul_f32 v[46:47], v[6:7], v[8:9]
	s_waitcnt lgkmcnt(7)
	v_mul_f32_e32 v6, 0x3fb8aa3b, v84
	v_mul_f32_e32 v7, 0x3fb8aa3b, v85
	ds_read2_b32 v[84:85], v117 offset0:36 offset1:37
	v_exp_f32_e32 v6, v6
	v_exp_f32_e32 v7, v7
	s_waitcnt lgkmcnt(7)
	v_pk_mul_f32 v[6:7], v[88:89], v[6:7]
	ds_read2_b32 v[88:89], v117 offset0:100 offset1:101
	s_waitcnt lgkmcnt(7)
	v_lshlrev_b32_e32 v8, 16, v92
	ds_read_u16 v92, v32 offset:26944
	s_waitcnt lgkmcnt(7)
	v_lshlrev_b32_e32 v9, 16, v96
	ds_read_u16 v96, v32 offset:27216
	v_pk_mul_f32 v[42:43], v[6:7], v[8:9]
	s_waitcnt lgkmcnt(7)
	v_mul_f32_e32 v6, 0x3fb8aa3b, v100
	v_mul_f32_e32 v7, 0x3fb8aa3b, v101
	ds_read2_b32 v[100:101], v117 offset0:38 offset1:39
	v_exp_f32_e32 v6, v6
	v_exp_f32_e32 v7, v7
	s_waitcnt lgkmcnt(7)
	v_pk_mul_f32 v[6:7], v[104:105], v[6:7]
	ds_read2_b32 v[104:105], v117 offset0:102 offset1:103
	s_waitcnt lgkmcnt(7)
	v_lshlrev_b32_e32 v8, 16, v108
	ds_read_u16 v108, v32 offset:27488
	s_waitcnt lgkmcnt(7)
	v_lshlrev_b32_e32 v9, 16, v112
	ds_read_u16 v112, v32 offset:27760
	v_pk_mul_f32 v[40:41], v[6:7], v[8:9]
	s_waitcnt lgkmcnt(7)
	v_mul_f32_e32 v6, 0x3fb8aa3b, v84
	v_mul_f32_e32 v7, 0x3fb8aa3b, v85
	ds_read2_b32 v[84:85], v117 offset0:40 offset1:41
	v_exp_f32_e32 v6, v6
	v_exp_f32_e32 v7, v7
	s_waitcnt lgkmcnt(7)
	v_pk_mul_f32 v[6:7], v[88:89], v[6:7]
	ds_read2_b32 v[88:89], v117 offset0:104 offset1:105
	s_waitcnt lgkmcnt(7)
	v_lshlrev_b32_e32 v8, 16, v92
	ds_read_u16 v92, v32 offset:28032
	s_waitcnt lgkmcnt(7)
	v_lshlrev_b32_e32 v9, 16, v96
	ds_read_u16 v96, v32 offset:28304
	v_pk_mul_f32 v[36:37], v[6:7], v[8:9]
	s_waitcnt lgkmcnt(7)
	v_mul_f32_e32 v6, 0x3fb8aa3b, v100
	v_mul_f32_e32 v7, 0x3fb8aa3b, v101
	ds_read2_b32 v[100:101], v117 offset0:42 offset1:43
	v_exp_f32_e32 v6, v6
	v_exp_f32_e32 v7, v7
	s_waitcnt lgkmcnt(7)
	v_pk_mul_f32 v[6:7], v[104:105], v[6:7]
	ds_read2_b32 v[104:105], v117 offset0:106 offset1:107
	s_waitcnt lgkmcnt(7)
	v_lshlrev_b32_e32 v8, 16, v108
	ds_read_u16 v108, v32 offset:28576
	s_waitcnt lgkmcnt(7)
	v_lshlrev_b32_e32 v9, 16, v112
	ds_read_u16 v112, v32 offset:28848
	v_pk_mul_f32 v[34:35], v[6:7], v[8:9]
	s_waitcnt lgkmcnt(7)
	v_mul_f32_e32 v6, 0x3fb8aa3b, v84
	v_mul_f32_e32 v7, 0x3fb8aa3b, v85
	ds_read2_b32 v[84:85], v117 offset0:44 offset1:45
	v_exp_f32_e32 v6, v6
	v_exp_f32_e32 v7, v7
	s_waitcnt lgkmcnt(7)
; #define LAS __attribute__((address_space(3)))
; __device__ __forceinline__ float bf2f(bf16_t v) { return __uint_as_float((unsigned)v << 16); }
; __device__ __forceinline__ void gd_prep_item(CArgs* a, LAS unsigned char* lds, int l, int item) {
;     ...
;             for (int t = 0; t < 64; ++t) x[t] = BETA[t] * __expf(GG[t]) * bf2f(*(const LAS bf16_t*)(lds + OFF_KN + t * PITCH + (col - 128) * 2)); }
	v_pk_mul_f32 v[6:7], v[88:89], v[6:7]
	ds_read2_b32 v[88:89], v117 offset0:108 offset1:109
	s_waitcnt lgkmcnt(7)
	v_lshlrev_b32_e32 v8, 16, v92
	ds_read_u16 v92, v32 offset:29120
	s_waitcnt lgkmcnt(7)
	v_lshlrev_b32_e32 v9, 16, v96
	ds_read_u16 v96, v32 offset:29392
	v_pk_mul_f32 v[30:31], v[6:7], v[8:9]
	s_waitcnt lgkmcnt(7)
	v_mul_f32_e32 v6, 0x3fb8aa3b, v100
	v_mul_f32_e32 v7, 0x3fb8aa3b, v101
	ds_read2_b32 v[100:101], v117 offset0:46 offset1:47
	v_exp_f32_e32 v6, v6
	v_exp_f32_e32 v7, v7
	s_waitcnt lgkmcnt(7)
	v_pk_mul_f32 v[6:7], v[104:105], v[6:7]
	ds_read2_b32 v[104:105], v117 offset0:110 offset1:111
	s_waitcnt lgkmcnt(7)
	v_lshlrev_b32_e32 v8, 16, v108
	ds_read_u16 v108, v32 offset:29664
	s_waitcnt lgkmcnt(7)
	v_lshlrev_b32_e32 v9, 16, v112
	ds_read_u16 v112, v32 offset:29936
	v_pk_mul_f32 v[26:27], v[6:7], v[8:9]
	s_waitcnt lgkmcnt(7)
	v_mul_f32_e32 v6, 0x3fb8aa3b, v84
	v_mul_f32_e32 v7, 0x3fb8aa3b, v85
	ds_read2_b32 v[84:85], v117 offset0:48 offset1:49
	v_exp_f32_e32 v6, v6
	v_exp_f32_e32 v7, v7
	s_waitcnt lgkmcnt(7)
	v_pk_mul_f32 v[6:7], v[88:89], v[6:7]
	ds_read2_b32 v[88:89], v117 offset0:112 offset1:113
	s_waitcnt lgkmcnt(7)
	v_lshlrev_b32_e32 v8, 16, v92
	ds_read_u16 v92, v32 offset:30208
	s_waitcnt lgkmcnt(7)
	v_lshlrev_b32_e32 v9, 16, v96
	ds_read_u16 v96, v32 offset:30480
	v_pk_mul_f32 v[24:25], v[6:7], v[8:9]
	s_waitcnt lgkmcnt(7)
	v_mul_f32_e32 v6, 0x3fb8aa3b, v100
	v_mul_f32_e32 v7, 0x3fb8aa3b, v101
	ds_read2_b32 v[100:101], v117 offset0:50 offset1:51
	v_exp_f32_e32 v6, v6
	v_exp_f32_e32 v7, v7
	s_waitcnt lgkmcnt(7)
	v_pk_mul_f32 v[6:7], v[104:105], v[6:7]
	ds_read2_b32 v[104:105], v117 offset0:114 offset1:115
	s_waitcnt lgkmcnt(7)
	v_lshlrev_b32_e32 v8, 16, v108
	ds_read_u16 v108, v32 offset:30752
	s_waitcnt lgkmcnt(7)
	v_lshlrev_b32_e32 v9, 16, v112
	ds_read_u16 v112, v32 offset:31024
	v_pk_mul_f32 v[20:21], v[6:7], v[8:9]
	s_waitcnt lgkmcnt(7)
	v_mul_f32_e32 v6, 0x3fb8aa3b, v84
	v_mul_f32_e32 v7, 0x3fb8aa3b, v85
	ds_read2_b32 v[84:85], v117 offset0:52 offset1:53
	v_exp_f32_e32 v6, v6
	v_exp_f32_e32 v7, v7
	s_waitcnt lgkmcnt(7)
	v_pk_mul_f32 v[6:7], v[88:89], v[6:7]
	ds_read2_b32 v[88:89], v117 offset0:116 offset1:117
	s_waitcnt lgkmcnt(7)
	v_lshlrev_b32_e32 v8, 16, v92
	ds_read_u16 v92, v32 offset:31296
	s_waitcnt lgkmcnt(7)
	v_lshlrev_b32_e32 v9, 16, v96
	ds_read_u16 v96, v32 offset:31568
	v_pk_mul_f32 v[18:19], v[6:7], v[8:9]
	s_waitcnt lgkmcnt(7)
	v_mul_f32_e32 v6, 0x3fb8aa3b, v100
	v_mul_f32_e32 v7, 0x3fb8aa3b, v101
	ds_read2_b32 v[100:101], v117 offset0:54 offset1:55
	v_exp_f32_e32 v6, v6
	v_exp_f32_e32 v7, v7
	s_waitcnt lgkmcnt(7)
	v_pk_mul_f32 v[6:7], v[104:105], v[6:7]
	ds_read2_b32 v[104:105], v117 offset0:118 offset1:119
	s_waitcnt lgkmcnt(7)
	v_lshlrev_b32_e32 v8, 16, v108
	ds_read_u16 v108, v32 offset:31840
	s_waitcnt lgkmcnt(7)
	v_lshlrev_b32_e32 v9, 16, v112
	ds_read_u16 v112, v32 offset:32112
	v_pk_mul_f32 v[14:15], v[6:7], v[8:9]
	s_waitcnt lgkmcnt(7)
	v_mul_f32_e32 v6, 0x3fb8aa3b, v84
	v_mul_f32_e32 v7, 0x3fb8aa3b, v85
	ds_read2_b32 v[84:85], v117 offset0:56 offset1:57
	v_exp_f32_e32 v6, v6
	v_exp_f32_e32 v7, v7
	s_waitcnt lgkmcnt(7)
	v_pk_mul_f32 v[6:7], v[88:89], v[6:7]
	ds_read2_b32 v[88:89], v117 offset0:120 offset1:121
	s_waitcnt lgkmcnt(7)
	v_lshlrev_b32_e32 v8, 16, v92
	ds_read_u16 v92, v32 offset:32384
	s_waitcnt lgkmcnt(7)
	v_lshlrev_b32_e32 v9, 16, v96
	ds_read_u16 v96, v32 offset:32656
	v_pk_mul_f32 v[10:11], v[6:7], v[8:9]
	s_waitcnt lgkmcnt(7)
	v_mul_f32_e32 v6, 0x3fb8aa3b, v100
	v_mul_f32_e32 v7, 0x3fb8aa3b, v101
	ds_read2_b32 v[100:101], v117 offset0:58 offset1:59
	v_exp_f32_e32 v6, v6
	v_exp_f32_e32 v7, v7
	s_waitcnt lgkmcnt(7)
	v_pk_mul_f32 v[6:7], v[104:105], v[6:7]
	ds_read2_b32 v[104:105], v117 offset0:122 offset1:123
	s_waitcnt lgkmcnt(7)
	v_lshlrev_b32_e32 v8, 16, v108
	ds_read_u16 v108, v32 offset:32928
	s_waitcnt lgkmcnt(7)
	v_lshlrev_b32_e32 v9, 16, v112
	ds_read_u16 v112, v32 offset:33200
	v_pk_mul_f32 v[8:9], v[6:7], v[8:9]
	s_waitcnt lgkmcnt(7)
	v_mul_f32_e32 v6, 0x3fb8aa3b, v84
	v_mul_f32_e32 v7, 0x3fb8aa3b, v85
	ds_read2_b32 v[84:85], v117 offset0:60 offset1:61
	v_exp_f32_e32 v6, v6
	v_exp_f32_e32 v7, v7
	s_nop 0
	s_waitcnt lgkmcnt(7)
	v_pk_mul_f32 v[6:7], v[88:89], v[6:7]
	ds_read2_b32 v[88:89], v117 offset0:124 offset1:125
	s_waitcnt lgkmcnt(7)
	v_lshlrev_b32_e32 v12, 16, v92
	ds_read_u16 v92, v32 offset:33472
	s_waitcnt lgkmcnt(7)
	v_lshlrev_b32_e32 v13, 16, v96
	ds_read_u16 v96, v32 offset:33744
	v_pk_mul_f32 v[6:7], v[6:7], v[12:13]
	s_waitcnt lgkmcnt(7)
	v_mul_f32_e32 v12, 0x3fb8aa3b, v100
	v_mul_f32_e32 v13, 0x3fb8aa3b, v101
	ds_read2_b32 v[100:101], v117 offset0:126 offset1:127
	v_exp_f32_e32 v12, v12
	v_exp_f32_e32 v13, v13
	s_nop 0
	s_waitcnt lgkmcnt(7)
	v_pk_mul_f32 v[12:13], v[104:105], v[12:13]
	ds_read_u16 v104, v32 offset:34016
	s_waitcnt lgkmcnt(7)
	v_lshlrev_b32_e32 v16, 16, v108
	ds_read_u16 v108, v32 offset:34288
	s_waitcnt lgkmcnt(7)
	v_lshlrev_b32_e32 v17, 16, v112
	v_pk_mul_f32 v[16:17], v[12:13], v[16:17]
	s_waitcnt lgkmcnt(6)
	v_mul_f32_e32 v12, 0x3fb8aa3b, v84
	v_mul_f32_e32 v13, 0x3fb8aa3b, v85
	v_exp_f32_e32 v12, v12
	v_exp_f32_e32 v13, v13
	s_nop 0
	s_waitcnt lgkmcnt(5)
	v_pk_mul_f32 v[12:13], v[88:89], v[12:13]
	s_waitcnt lgkmcnt(4)
	v_lshlrev_b32_e32 v28, 16, v92
	s_waitcnt lgkmcnt(3)
	v_lshlrev_b32_e32 v29, 16, v96
	v_pk_mul_f32 v[12:13], v[12:13], v[28:29]
	s_waitcnt lgkmcnt(2)
	v_pk_mul_f32 v[22:23], v[100:101], v[22:23]
	s_waitcnt lgkmcnt(1)
	v_lshlrev_b32_e32 v28, 16, v104
	s_waitcnt lgkmcnt(0)
	v_lshlrev_b32_e32 v29, 16, v108
	v_pk_mul_f32 v[22:23], v[22:23], v[28:29]
; __device__ __forceinline__ void gd_prep_item(CArgs* a, LAS unsigned char* lds, int l, int item) {
;     ...
;     if (wid < 4) {
;         const int col = tid; float x[64];
;         if (col < 128) {
; #pragma unroll
;             for (int t = 0; t < 64; ++t) x[t] = BETA[t] * V[t * 128 + col]; }
.LBB0_987:
	s_andn2_saveexec_b64 s[10:11], s[10:11]
	s_cbranch_execz .LBB0_989
	v_lshl_add_u32 v22, v3, 2, v118
	ds_read2st64_b32 v[84:85], v22 offset1:2
	ds_read2st64_b32 v[88:89], v22 offset0:4 offset1:6
	ds_read2_b32 v[92:93], v117 offset0:66 offset1:67
	ds_read2st64_b32 v[96:97], v22 offset0:8 offset1:10
	ds_read2_b32 v[100:101], v117 offset0:68 offset1:69
	ds_read2st64_b32 v[104:105], v22 offset0:12 offset1:14
	ds_read2_b32 v[108:109], v117 offset0:70 offset1:71
	ds_read2st64_b32 v[112:113], v22 offset0:16 offset1:18
	ds_read_b32 v28, v117 offset:260
	s_waitcnt lgkmcnt(8)
	v_mov_b32_e32 v6, v85
	v_mov_b32_e32 v7, v84
	ds_read2_b32 v[84:85], v117 offset0:72 offset1:73
	s_waitcnt lgkmcnt(1)
	v_pk_mul_f32 v[4:5], v[28:29], v[6:7]
	v_pk_mul_f32 v[70:71], v[92:93], v[88:89]
	ds_read2st64_b32 v[88:89], v22 offset0:20 offset1:22
	ds_read2_b32 v[92:93], v117 offset0:74 offset1:75
	v_pk_mul_f32 v[74:75], v[100:101], v[96:97]
	ds_read2st64_b32 v[96:97], v22 offset0:24 offset1:26
	ds_read2_b32 v[100:101], v117 offset0:76 offset1:77
	v_pk_mul_f32 v[80:81], v[108:109], v[104:105]
	ds_read2st64_b32 v[104:105], v22 offset0:28 offset1:30
	ds_read2_b32 v[108:109], v117 offset0:78 offset1:79
	s_waitcnt lgkmcnt(6)
	v_pk_mul_f32 v[78:79], v[84:85], v[112:113]
	ds_read2st64_b32 v[112:113], v22 offset0:32 offset1:34
	ds_read2_b32 v[84:85], v117 offset0:80 offset1:81
	s_waitcnt lgkmcnt(6)
	v_pk_mul_f32 v[76:77], v[92:93], v[88:89]
	ds_read2st64_b32 v[88:89], v22 offset0:36 offset1:38
	ds_read2_b32 v[92:93], v117 offset0:82 offset1:83
	s_waitcnt lgkmcnt(6)
	v_pk_mul_f32 v[72:73], v[100:101], v[96:97]
	ds_read2st64_b32 v[96:97], v22 offset0:40 offset1:42
	ds_read2_b32 v[100:101], v117 offset0:84 offset1:85
	s_waitcnt lgkmcnt(6)
	v_pk_mul_f32 v[66:67], v[108:109], v[104:105]
	ds_read2st64_b32 v[104:105], v22 offset0:44 offset1:46
	ds_read2_b32 v[108:109], v117 offset0:86 offset1:87
	s_waitcnt lgkmcnt(6)
	v_pk_mul_f32 v[64:65], v[84:85], v[112:113]
	ds_read2st64_b32 v[112:113], v22 offset0:48 offset1:50
	ds_read2_b32 v[84:85], v117 offset0:88 offset1:89
	s_waitcnt lgkmcnt(6)
	v_pk_mul_f32 v[62:63], v[92:93], v[88:89]
	ds_read2st64_b32 v[88:89], v22 offset0:52 offset1:54
	ds_read2_b32 v[92:93], v117 offset0:90 offset1:91
	s_waitcnt lgkmcnt(6)
	v_pk_mul_f32 v[60:61], v[100:101], v[96:97]
	ds_read2st64_b32 v[96:97], v22 offset0:56 offset1:58
	ds_read2_b32 v[100:101], v117 offset0:92 offset1:93
	s_waitcnt lgkmcnt(6)
	v_pk_mul_f32 v[56:57], v[108:109], v[104:105]
	ds_read2st64_b32 v[104:105], v22 offset0:60 offset1:62
	ds_read2_b32 v[108:109], v117 offset0:94 offset1:95
	s_waitcnt lgkmcnt(6)
	v_pk_mul_f32 v[54:55], v[84:85], v[112:113]
	ds_read2st64_b32 v[112:113], v22 offset0:64 offset1:66
	ds_read2_b32 v[84:85], v117 offset0:96 offset1:97
	s_waitcnt lgkmcnt(6)
	v_pk_mul_f32 v[52:53], v[92:93], v[88:89]
	ds_read2st64_b32 v[88:89], v22 offset0:68 offset1:70
	ds_read2_b32 v[92:93], v117 offset0:98 offset1:99
	s_waitcnt lgkmcnt(6)
	v_pk_mul_f32 v[48:49], v[100:101], v[96:97]
	ds_read2st64_b32 v[96:97], v22 offset0:72 offset1:74
	ds_read2_b32 v[100:101], v117 offset0:100 offset1:101
	s_waitcnt lgkmcnt(6)
	v_pk_mul_f32 v[46:47], v[108:109], v[104:105]
	ds_read2st64_b32 v[104:105], v22 offset0:76 offset1:78
	ds_read2_b32 v[108:109], v117 offset0:102 offset1:103
	s_waitcnt lgkmcnt(6)
	v_pk_mul_f32 v[42:43], v[84:85], v[112:113]
	ds_read2st64_b32 v[112:113], v22 offset0:80 offset1:82
	ds_read2_b32 v[84:85], v117 offset0:104 offset1:105
	s_waitcnt lgkmcnt(6)
	v_pk_mul_f32 v[40:41], v[92:93], v[88:89]
	ds_read2st64_b32 v[88:89], v22 offset0:84 offset1:86
	ds_read2_b32 v[92:93], v117 offset0:106 offset1:107
	s_waitcnt lgkmcnt(6)
	v_pk_mul_f32 v[36:37], v[100:101], v[96:97]
	ds_read2st64_b32 v[96:97], v22 offset0:88 offset1:90
	ds_read2_b32 v[100:101], v117 offset0:108 offset1:109
	s_waitcnt lgkmcnt(6)
	v_pk_mul_f32 v[34:35], v[108:109], v[104:105]
	ds_read2st64_b32 v[104:105], v22 offset0:92 offset1:94
	ds_read2_b32 v[108:109], v117 offset0:110 offset1:111
	s_waitcnt lgkmcnt(6)
	v_pk_mul_f32 v[30:31], v[84:85], v[112:113]
	ds_read2st64_b32 v[112:113], v22 offset0:96 offset1:98
	ds_read2_b32 v[84:85], v117 offset0:112 offset1:113
	s_waitcnt lgkmcnt(6)
	v_pk_mul_f32 v[26:27], v[92:93], v[88:89]
	ds_read2st64_b32 v[88:89], v22 offset0:100 offset1:102
	ds_read2_b32 v[92:93], v117 offset0:114 offset1:115
	s_waitcnt lgkmcnt(6)
	v_pk_mul_f32 v[24:25], v[100:101], v[96:97]
	ds_read2st64_b32 v[96:97], v22 offset0:104 offset1:106
	ds_read2_b32 v[100:101], v117 offset0:116 offset1:117
	s_waitcnt lgkmcnt(6)
	v_pk_mul_f32 v[20:21], v[108:109], v[104:105]
	ds_read2st64_b32 v[104:105], v22 offset0:108 offset1:110
	ds_read2_b32 v[108:109], v117 offset0:118 offset1:119
	s_waitcnt lgkmcnt(6)
	v_pk_mul_f32 v[18:19], v[84:85], v[112:113]
	ds_read2st64_b32 v[112:113], v22 offset0:112 offset1:114
	ds_read2_b32 v[84:85], v117 offset0:120 offset1:121
	s_waitcnt lgkmcnt(6)
	v_pk_mul_f32 v[14:15], v[92:93], v[88:89]
	ds_read2st64_b32 v[88:89], v22 offset0:116 offset1:118
	ds_read2_b32 v[92:93], v117 offset0:122 offset1:123
	s_waitcnt lgkmcnt(6)
	v_pk_mul_f32 v[10:11], v[100:101], v[96:97]
	ds_read2st64_b32 v[96:97], v22 offset0:120 offset1:122
	ds_read2_b32 v[100:101], v117 offset0:124 offset1:125
	s_waitcnt lgkmcnt(6)
	v_pk_mul_f32 v[8:9], v[108:109], v[104:105]
	ds_read2st64_b32 v[104:105], v22 offset0:124 offset1:126
	ds_read2_b32 v[108:109], v117 offset0:126 offset1:127
	s_waitcnt lgkmcnt(6)
	v_pk_mul_f32 v[6:7], v[84:85], v[112:113]
	s_waitcnt lgkmcnt(4)
	v_pk_mul_f32 v[16:17], v[92:93], v[88:89]
	s_waitcnt lgkmcnt(2)
	v_pk_mul_f32 v[12:13], v[100:101], v[96:97]
	s_waitcnt lgkmcnt(0)
	v_pk_mul_f32 v[22:23], v[108:109], v[104:105]
